# MoBA loop: DMA issue moved off the top for both groups (group 0 after 2 MFMAs, group 1 after 10 MFMAs)
# baseline (speedup 1.0000x reference)
; __device__ __forceinline__ void pv(f32x16* o, int vb, bf16x8 pa0, bf16x8 pa1, bf16x8 pa2, bf16x8 pa3) {
; #pragma unroll
;     for (int d0 = 0; d0 < 2; ++d0) { s16x4 lo[4], hi[4];
; #pragma unroll
;         for (int ks = 0; ks < 4; ++ks) {
;             asm volatile("ds_read_b64_tr_b16 %0,%1 offset:%c2" : "=&v"(lo[ks]) : "v"(vb), "i"(d0 * 4096 + ks * 1024) : "memory");
;             asm volatile("ds_read_b64_tr_b16 %0,%1 offset:%c2" : "=&v"(hi[ks]) : "v"(vb), "i"(d0 * 4096 + ks * 1024 + 512) : "memory"); }
;         asm volatile("s_waitcnt lgkmcnt(0)" ::: "memory"); __builtin_amdgcn_sched_barrier(0);
.LBB0_1059:
.LBB0_1060:
.LBB0_1062:
.Lmb1_A:
	s_barrier
	s_add_i32 s42, s44, 0x2000
	s_add_i32 s98, s44, 0x4000
	s_and_b32 s45, s98, 0x6000
	v_add_u32_e32 v133, s45, v130
	ds_read_b128 v[154:157], v133
	ds_read_b128 v[158:161], v133 offset:512
	ds_read_b128 v[162:165], v133 offset:2048
	ds_read_b128 v[166:169], v133 offset:2560
	ds_read_b128 v[170:173], v133 offset:4096
	ds_read_b128 v[174:177], v133 offset:4608
	ds_read_b128 v[178:181], v133 offset:6144
	ds_read_b128 v[182:185], v133 offset:6656
	s_and_b32 s45, s42, 0x6000
	v_add_u32_e32 v218, s45, v132
	s_add_i32 s98, s34, 2
	s_cmp_ge_i32 s34, s31
	s_cbranch_scc1 .Lmb1_A_near
	v_mfma_f32_32x32x16_bf16 v[16:31], v[108:111], v[186:189], v[16:31]
	v_exp_f32_e32 v64, v64
	v_exp_f32_e32 v48, v48
	v_mfma_f32_32x32x16_bf16 v[16:31], v[104:107], v[190:193], v[16:31]
	v_exp_f32_e32 v65, v65
	v_exp_f32_e32 v49, v49
	v_add_f32_e32 v252, v64, v48
	s_and_b64 vcc, exec, s[6:7]
	s_cbranch_vccz .Lmb1_A_g1skip
	s_add_i32 s45, s37, 1
	s_cmp_ge_u32 s45, s30
	s_cbranch_scc1 .Lmb1_skKAg
	s_add_i32 s45, s44, 0x2000
	s_and_b32 s45, s45, 0x6000
	s_add_i32 s45, s45, s74
	s_mov_b32 s99, m0
	s_mov_b32 m0, s45
	s_nop 0
	global_load_lds_dwordx4 v[114:115], off
	s_mov_b32 m0, s99
	s_mov_b32 s43, 1

; #define ATT_LAS __attribute__((address_space(3)))
; #define ATT_MFMA(a, b, c) __builtin_amdgcn_mfma_f32_32x32x16_bf16((a), (b), (c), 0, 0, 0)
; __device__ __forceinline__ void qkt(f32x16& p0, f32x16& p1, lds_cptr kb, const bf16x8* qr, const f32x16& z) {
; #pragma unroll
;     for (int d0 = 0; d0 < 4; ++d0) {
;         const bf16x8 b0 = *(const ATT_LAS bf16x8*)(kb + d0 * 2048);
;         const bf16x8 b1 = *(const ATT_LAS bf16x8*)(kb + d0 * 2048 + 512);
;         if (d0 == 0) { p0 = ATT_MFMA(b0, qr[0], z); p1 = ATT_MFMA(b1, qr[0], z); }
;         else { p0 = ATT_MFMA(b0, qr[d0], p0); p1 = ATT_MFMA(b1, qr[d0], p1); } }
; __device__ __forceinline__ void pv(f32x16* o, int vb, bf16x8 pa0, bf16x8 pa1, bf16x8 pa2, bf16x8 pa3) {
; #pragma unroll
;     for (int d0 = 0; d0 < 2; ++d0) { s16x4 lo[4], hi[4];
; #pragma unroll
;         for (int ks = 0; ks < 4; ++ks) {
;             asm volatile("ds_read_b64_tr_b16 %0,%1 offset:%c2" : "=&v"(lo[ks]) : "v"(vb), "i"(d0 * 4096 + ks * 1024) : "memory");
;             asm volatile("ds_read_b64_tr_b16 %0,%1 offset:%c2" : "=&v"(hi[ks]) : "v"(vb), "i"(d0 * 4096 + ks * 1024 + 512) : "memory"); }
;         asm volatile("s_waitcnt lgkmcnt(0)" ::: "memory"); __builtin_amdgcn_sched_barrier(0);
;     ...
;         o[d0] = ATT_MFMA(pa0, ATT_PK(0), o[d0]);
;         o[d0] = ATT_MFMA(pa1, ATT_PK(1), o[d0]);
;         o[d0] = ATT_MFMA(pa2, ATT_PK(2), o[d0]);
;         o[d0] = ATT_MFMA(pa3, ATT_PK(3), o[d0]);
;     ...
;     }
; }
.Lmb1_skVAg:
.Lmb1_A_g1skip:
	v_mfma_f32_32x32x16_bf16 v[16:31], v[100:103], v[194:197], v[16:31]
	v_exp_f32_e32 v66, v66
	v_exp_f32_e32 v50, v50
	v_add_f32_e32 v253, v65, v49
	v_add_f32_e32 v252, v252, v253
	v_mfma_f32_32x32x16_bf16 v[16:31], v[96:99], v[198:201], v[16:31]
	v_exp_f32_e32 v67, v67
	v_exp_f32_e32 v51, v51
	v_add_f32_e32 v253, v66, v50
	v_add_f32_e32 v252, v252, v253
	v_mfma_f32_32x32x16_bf16 v[32:47], v[108:111], v[202:205], v[32:47]
	v_exp_f32_e32 v68, v68
	v_exp_f32_e32 v52, v52
	v_add_f32_e32 v253, v67, v51
	v_add_f32_e32 v252, v252, v253
	ds_read_b64_tr_b16 v[186:187], v218
	ds_read_b64_tr_b16 v[188:189], v218 offset:512
	v_mfma_f32_32x32x16_bf16 v[32:47], v[104:107], v[206:209], v[32:47]
	v_exp_f32_e32 v69, v69
	v_exp_f32_e32 v53, v53
	v_add_f32_e32 v253, v68, v52
	v_add_f32_e32 v252, v252, v253
	ds_read_b64_tr_b16 v[190:191], v218 offset:1024
	ds_read_b64_tr_b16 v[192:193], v218 offset:1536
	v_mfma_f32_32x32x16_bf16 v[32:47], v[100:103], v[210:213], v[32:47]
	v_exp_f32_e32 v70, v70
	v_exp_f32_e32 v54, v54
	v_add_f32_e32 v253, v69, v53
	v_add_f32_e32 v252, v252, v253
	ds_read_b64_tr_b16 v[194:195], v218 offset:2048
	ds_read_b64_tr_b16 v[196:197], v218 offset:2560
	v_mfma_f32_32x32x16_bf16 v[32:47], v[96:99], v[214:217], v[32:47]
	v_exp_f32_e32 v71, v71
	v_exp_f32_e32 v55, v55
	v_add_f32_e32 v253, v70, v54
	v_add_f32_e32 v252, v252, v253
	ds_read_b64_tr_b16 v[198:199], v218 offset:3072
	ds_read_b64_tr_b16 v[200:201], v218 offset:3584
	s_waitcnt lgkmcnt(8)
	v_mfma_f32_32x32x16_bf16 v[236:251], v[154:157], v[92:95], v[220:235]
	v_exp_f32_e32 v72, v72
	v_exp_f32_e32 v56, v56
	v_add_f32_e32 v253, v71, v55
	v_add_f32_e32 v252, v252, v253
	v_cvt_pk_bf16_f32 v108, v64, v65
	v_cvt_pk_bf16_f32 v100, v48, v49
	ds_read_b64_tr_b16 v[202:203], v218 offset:4096
	ds_read_b64_tr_b16 v[204:205], v218 offset:4608
	v_mfma_f32_32x32x16_bf16 v[134:149], v[158:161], v[92:95], v[220:235]
	v_exp_f32_e32 v73, v73
	v_exp_f32_e32 v57, v57
	v_add_f32_e32 v253, v72, v56
	v_add_f32_e32 v252, v252, v253
	v_cvt_pk_bf16_f32 v109, v66, v67
	v_cvt_pk_bf16_f32 v101, v50, v51
	ds_read_b64_tr_b16 v[206:207], v218 offset:5120
	ds_read_b64_tr_b16 v[208:209], v218 offset:5632
	s_and_b64 vcc, exec, s[6:7]
	s_cbranch_vccnz .Lmb1_A_g0mid
	s_add_i32 s45, s37, 1
	s_cmp_ge_u32 s45, s30
	s_cbranch_scc1 .Lmb1_skKAm
	s_add_i32 s45, s44, 0x2000
	s_and_b32 s45, s45, 0x6000
	s_add_i32 s45, s45, s74
	s_mov_b32 s99, m0
	s_mov_b32 m0, s45
	s_nop 0
	global_load_lds_dwordx4 v[114:115], off
	s_mov_b32 m0, s99
	s_mov_b32 s43, 1

; #define ATT_LAS __attribute__((address_space(3)))
; #define ATT_MFMA(a, b, c) __builtin_amdgcn_mfma_f32_32x32x16_bf16((a), (b), (c), 0, 0, 0)
; __device__ __forceinline__ void qkt(f32x16& p0, f32x16& p1, lds_cptr kb, const bf16x8* qr, const f32x16& z) {
; #pragma unroll
;     for (int d0 = 0; d0 < 4; ++d0) {
;         const bf16x8 b0 = *(const ATT_LAS bf16x8*)(kb + d0 * 2048);
;         const bf16x8 b1 = *(const ATT_LAS bf16x8*)(kb + d0 * 2048 + 512);
;         if (d0 == 0) { p0 = ATT_MFMA(b0, qr[0], z); p1 = ATT_MFMA(b1, qr[0], z); }
;         else { p0 = ATT_MFMA(b0, qr[d0], p0); p1 = ATT_MFMA(b1, qr[d0], p1); } }
.Lmb1_skVAm:
.Lmb1_A_g0mid:
	v_mfma_f32_32x32x16_bf16 v[236:251], v[162:165], v[88:91], v[236:251]
	v_exp_f32_e32 v74, v74
	v_exp_f32_e32 v58, v58
	v_add_f32_e32 v253, v73, v57
	v_add_f32_e32 v252, v252, v253
	v_cvt_pk_bf16_f32 v110, v68, v69
	v_cvt_pk_bf16_f32 v102, v52, v53
	ds_read_b64_tr_b16 v[210:211], v218 offset:6144
	ds_read_b64_tr_b16 v[212:213], v218 offset:6656
	v_mfma_f32_32x32x16_bf16 v[134:149], v[166:169], v[88:91], v[134:149]
	v_exp_f32_e32 v75, v75
	v_exp_f32_e32 v59, v59
	v_add_f32_e32 v253, v74, v58
	v_add_f32_e32 v252, v252, v253
	v_cvt_pk_bf16_f32 v111, v70, v71
	v_cvt_pk_bf16_f32 v103, v54, v55
	ds_read_b64_tr_b16 v[214:215], v218 offset:7168
	ds_read_b64_tr_b16 v[216:217], v218 offset:7680
	v_mfma_f32_32x32x16_bf16 v[236:251], v[170:173], v[84:87], v[236:251]
	v_exp_f32_e32 v76, v76
	v_exp_f32_e32 v60, v60
	v_add_f32_e32 v253, v75, v59
	v_add_f32_e32 v252, v252, v253
	v_cvt_pk_bf16_f32 v104, v72, v73
	v_cvt_pk_bf16_f32 v96, v56, v57
	v_mfma_f32_32x32x16_bf16 v[134:149], v[174:177], v[84:87], v[134:149]
	v_exp_f32_e32 v77, v77
	v_exp_f32_e32 v61, v61
	v_add_f32_e32 v253, v76, v60
	v_add_f32_e32 v252, v252, v253
	v_cvt_pk_bf16_f32 v105, v74, v75
	v_cvt_pk_bf16_f32 v97, v58, v59
	v_mfma_f32_32x32x16_bf16 v[236:251], v[178:181], v[80:83], v[236:251]
	v_exp_f32_e32 v78, v78
	v_exp_f32_e32 v62, v62
	v_add_f32_e32 v253, v77, v61
	v_add_f32_e32 v252, v252, v253
	v_cvt_pk_bf16_f32 v106, v76, v77
	v_cvt_pk_bf16_f32 v98, v60, v61
	v_mfma_f32_32x32x16_bf16 v[134:149], v[182:185], v[80:83], v[134:149]
	v_exp_f32_e32 v79, v79
	v_exp_f32_e32 v63, v63
	v_add_f32_e32 v253, v78, v62
	v_add_f32_e32 v252, v252, v253
	v_add_f32_e32 v253, v79, v63
	v_add_f32_e32 v252, v252, v253
	v_cvt_pk_bf16_f32 v107, v78, v79
	v_cvt_pk_bf16_f32 v99, v62, v63
	v_add_f32_e32 v131, v131, v252

; __device__ __forceinline__ void pv(f32x16* o, int vb, bf16x8 pa0, bf16x8 pa1, bf16x8 pa2, bf16x8 pa3) {
; #pragma unroll
;     for (int d0 = 0; d0 < 2; ++d0) { s16x4 lo[4], hi[4];
; #pragma unroll
;         for (int ks = 0; ks < 4; ++ks) {
;             asm volatile("ds_read_b64_tr_b16 %0,%1 offset:%c2" : "=&v"(lo[ks]) : "v"(vb), "i"(d0 * 4096 + ks * 1024) : "memory");
;             asm volatile("ds_read_b64_tr_b16 %0,%1 offset:%c2" : "=&v"(hi[ks]) : "v"(vb), "i"(d0 * 4096 + ks * 1024 + 512) : "memory"); }
;         asm volatile("s_waitcnt lgkmcnt(0)" ::: "memory"); __builtin_amdgcn_sched_barrier(0);
.Lmb1_B:
	s_barrier
	s_add_i32 s42, s44, 0x2000
	s_add_i32 s98, s44, 0x4000
	s_and_b32 s45, s98, 0x6000
	v_add_u32_e32 v133, s45, v130
	ds_read_b128 v[154:157], v133
	ds_read_b128 v[158:161], v133 offset:512
	ds_read_b128 v[162:165], v133 offset:2048
	ds_read_b128 v[166:169], v133 offset:2560
	ds_read_b128 v[170:173], v133 offset:4096
	ds_read_b128 v[174:177], v133 offset:4608
	ds_read_b128 v[178:181], v133 offset:6144
	ds_read_b128 v[182:185], v133 offset:6656
	s_and_b32 s45, s42, 0x6000
	v_add_u32_e32 v218, s45, v132
	s_add_i32 s98, s34, 2
	s_cmp_ge_i32 s34, s31
	s_cbranch_scc1 .Lmb1_B_near
	v_mfma_f32_32x32x16_bf16 v[16:31], v[108:111], v[186:189], v[16:31]
	v_exp_f32_e32 v236, v236
	v_exp_f32_e32 v134, v134
	v_mfma_f32_32x32x16_bf16 v[16:31], v[104:107], v[190:193], v[16:31]
	v_exp_f32_e32 v237, v237
	v_exp_f32_e32 v135, v135
	v_add_f32_e32 v252, v236, v134
	s_and_b64 vcc, exec, s[6:7]
	s_cbranch_vccz .Lmb1_B_g1skip
	s_add_i32 s45, s37, 1
	s_cmp_ge_u32 s45, s30
	s_cbranch_scc1 .Lmb1_skKBg
	s_add_i32 s45, s44, 0x2000
	s_and_b32 s45, s45, 0x6000
	s_add_i32 s45, s45, s74
	s_mov_b32 s99, m0
	s_mov_b32 m0, s45
	s_nop 0
	global_load_lds_dwordx4 v[114:115], off
	s_mov_b32 m0, s99
	s_mov_b32 s43, 1

; #define ATT_LAS __attribute__((address_space(3)))
; #define ATT_MFMA(a, b, c) __builtin_amdgcn_mfma_f32_32x32x16_bf16((a), (b), (c), 0, 0, 0)
; __device__ __forceinline__ void qkt(f32x16& p0, f32x16& p1, lds_cptr kb, const bf16x8* qr, const f32x16& z) {
; #pragma unroll
;     for (int d0 = 0; d0 < 4; ++d0) {
;         const bf16x8 b0 = *(const ATT_LAS bf16x8*)(kb + d0 * 2048);
;         const bf16x8 b1 = *(const ATT_LAS bf16x8*)(kb + d0 * 2048 + 512);
;         if (d0 == 0) { p0 = ATT_MFMA(b0, qr[0], z); p1 = ATT_MFMA(b1, qr[0], z); }
;         else { p0 = ATT_MFMA(b0, qr[d0], p0); p1 = ATT_MFMA(b1, qr[d0], p1); } }
; __device__ __forceinline__ void pv(f32x16* o, int vb, bf16x8 pa0, bf16x8 pa1, bf16x8 pa2, bf16x8 pa3) {
; #pragma unroll
;     for (int d0 = 0; d0 < 2; ++d0) { s16x4 lo[4], hi[4];
; #pragma unroll
;         for (int ks = 0; ks < 4; ++ks) {
;             asm volatile("ds_read_b64_tr_b16 %0,%1 offset:%c2" : "=&v"(lo[ks]) : "v"(vb), "i"(d0 * 4096 + ks * 1024) : "memory");
;             asm volatile("ds_read_b64_tr_b16 %0,%1 offset:%c2" : "=&v"(hi[ks]) : "v"(vb), "i"(d0 * 4096 + ks * 1024 + 512) : "memory"); }
;         asm volatile("s_waitcnt lgkmcnt(0)" ::: "memory"); __builtin_amdgcn_sched_barrier(0);
;     ...
;         o[d0] = ATT_MFMA(pa0, ATT_PK(0), o[d0]);
;         o[d0] = ATT_MFMA(pa1, ATT_PK(1), o[d0]);
;         o[d0] = ATT_MFMA(pa2, ATT_PK(2), o[d0]);
;         o[d0] = ATT_MFMA(pa3, ATT_PK(3), o[d0]);
;     ...
;     }
; }
.Lmb1_skVBg:
.Lmb1_B_g1skip:
	v_mfma_f32_32x32x16_bf16 v[16:31], v[100:103], v[194:197], v[16:31]
	v_exp_f32_e32 v238, v238
	v_exp_f32_e32 v136, v136
	v_add_f32_e32 v253, v237, v135
	v_add_f32_e32 v252, v252, v253
	v_mfma_f32_32x32x16_bf16 v[16:31], v[96:99], v[198:201], v[16:31]
	v_exp_f32_e32 v239, v239
	v_exp_f32_e32 v137, v137
	v_add_f32_e32 v253, v238, v136
	v_add_f32_e32 v252, v252, v253
	v_mfma_f32_32x32x16_bf16 v[32:47], v[108:111], v[202:205], v[32:47]
	v_exp_f32_e32 v240, v240
	v_exp_f32_e32 v138, v138
	v_add_f32_e32 v253, v239, v137
	v_add_f32_e32 v252, v252, v253
	ds_read_b64_tr_b16 v[186:187], v218
	ds_read_b64_tr_b16 v[188:189], v218 offset:512
	v_mfma_f32_32x32x16_bf16 v[32:47], v[104:107], v[206:209], v[32:47]
	v_exp_f32_e32 v241, v241
	v_exp_f32_e32 v139, v139
	v_add_f32_e32 v253, v240, v138
	v_add_f32_e32 v252, v252, v253
	ds_read_b64_tr_b16 v[190:191], v218 offset:1024
	ds_read_b64_tr_b16 v[192:193], v218 offset:1536
	v_mfma_f32_32x32x16_bf16 v[32:47], v[100:103], v[210:213], v[32:47]
	v_exp_f32_e32 v242, v242
	v_exp_f32_e32 v140, v140
	v_add_f32_e32 v253, v241, v139
	v_add_f32_e32 v252, v252, v253
	ds_read_b64_tr_b16 v[194:195], v218 offset:2048
	ds_read_b64_tr_b16 v[196:197], v218 offset:2560
	v_mfma_f32_32x32x16_bf16 v[32:47], v[96:99], v[214:217], v[32:47]
	v_exp_f32_e32 v243, v243
	v_exp_f32_e32 v141, v141
	v_add_f32_e32 v253, v242, v140
	v_add_f32_e32 v252, v252, v253
	ds_read_b64_tr_b16 v[198:199], v218 offset:3072
	ds_read_b64_tr_b16 v[200:201], v218 offset:3584
	s_waitcnt lgkmcnt(8)
	v_mfma_f32_32x32x16_bf16 v[64:79], v[154:157], v[92:95], v[220:235]
	v_exp_f32_e32 v244, v244
	v_exp_f32_e32 v142, v142
	v_add_f32_e32 v253, v243, v141
	v_add_f32_e32 v252, v252, v253
	v_cvt_pk_bf16_f32 v108, v236, v237
	v_cvt_pk_bf16_f32 v100, v134, v135
	ds_read_b64_tr_b16 v[202:203], v218 offset:4096
	ds_read_b64_tr_b16 v[204:205], v218 offset:4608
	v_mfma_f32_32x32x16_bf16 v[48:63], v[158:161], v[92:95], v[220:235]
	v_exp_f32_e32 v245, v245
	v_exp_f32_e32 v143, v143
	v_add_f32_e32 v253, v244, v142
	v_add_f32_e32 v252, v252, v253
	v_cvt_pk_bf16_f32 v109, v238, v239
	v_cvt_pk_bf16_f32 v101, v136, v137
	ds_read_b64_tr_b16 v[206:207], v218 offset:5120
	ds_read_b64_tr_b16 v[208:209], v218 offset:5632
	s_and_b64 vcc, exec, s[6:7]
	s_cbranch_vccnz .Lmb1_B_g0mid
	s_add_i32 s45, s37, 1
	s_cmp_ge_u32 s45, s30
	s_cbranch_scc1 .Lmb1_skKBm
	s_add_i32 s45, s44, 0x2000
	s_and_b32 s45, s45, 0x6000
	s_add_i32 s45, s45, s74
	s_mov_b32 s99, m0
	s_mov_b32 m0, s45
	s_nop 0
	global_load_lds_dwordx4 v[114:115], off
	s_mov_b32 m0, s99
	s_mov_b32 s43, 1

; #define ATT_LAS __attribute__((address_space(3)))
; #define ATT_MFMA(a, b, c) __builtin_amdgcn_mfma_f32_32x32x16_bf16((a), (b), (c), 0, 0, 0)
; __device__ __forceinline__ void qkt(f32x16& p0, f32x16& p1, lds_cptr kb, const bf16x8* qr, const f32x16& z) {
; #pragma unroll
;     for (int d0 = 0; d0 < 4; ++d0) {
;         const bf16x8 b0 = *(const ATT_LAS bf16x8*)(kb + d0 * 2048);
;         const bf16x8 b1 = *(const ATT_LAS bf16x8*)(kb + d0 * 2048 + 512);
;         if (d0 == 0) { p0 = ATT_MFMA(b0, qr[0], z); p1 = ATT_MFMA(b1, qr[0], z); }
;         else { p0 = ATT_MFMA(b0, qr[d0], p0); p1 = ATT_MFMA(b1, qr[d0], p1); } }
.Lmb1_skVBm:
.Lmb1_B_g0mid:
	v_mfma_f32_32x32x16_bf16 v[64:79], v[162:165], v[88:91], v[64:79]
	v_exp_f32_e32 v246, v246
	v_exp_f32_e32 v144, v144
	v_add_f32_e32 v253, v245, v143
	v_add_f32_e32 v252, v252, v253
	v_cvt_pk_bf16_f32 v110, v240, v241
	v_cvt_pk_bf16_f32 v102, v138, v139
	ds_read_b64_tr_b16 v[210:211], v218 offset:6144
	ds_read_b64_tr_b16 v[212:213], v218 offset:6656
	v_mfma_f32_32x32x16_bf16 v[48:63], v[166:169], v[88:91], v[48:63]
	v_exp_f32_e32 v247, v247
	v_exp_f32_e32 v145, v145
	v_add_f32_e32 v253, v246, v144
	v_add_f32_e32 v252, v252, v253
	v_cvt_pk_bf16_f32 v111, v242, v243
	v_cvt_pk_bf16_f32 v103, v140, v141
	ds_read_b64_tr_b16 v[214:215], v218 offset:7168
	ds_read_b64_tr_b16 v[216:217], v218 offset:7680
	v_mfma_f32_32x32x16_bf16 v[64:79], v[170:173], v[84:87], v[64:79]
	v_exp_f32_e32 v248, v248
	v_exp_f32_e32 v146, v146
	v_add_f32_e32 v253, v247, v145
	v_add_f32_e32 v252, v252, v253
	v_cvt_pk_bf16_f32 v104, v244, v245
	v_cvt_pk_bf16_f32 v96, v142, v143
	v_mfma_f32_32x32x16_bf16 v[48:63], v[174:177], v[84:87], v[48:63]
	v_exp_f32_e32 v249, v249
	v_exp_f32_e32 v147, v147
	v_add_f32_e32 v253, v248, v146
	v_add_f32_e32 v252, v252, v253
	v_cvt_pk_bf16_f32 v105, v246, v247
	v_cvt_pk_bf16_f32 v97, v144, v145
	v_mfma_f32_32x32x16_bf16 v[64:79], v[178:181], v[80:83], v[64:79]
	v_exp_f32_e32 v250, v250
	v_exp_f32_e32 v148, v148
	v_add_f32_e32 v253, v249, v147
	v_add_f32_e32 v252, v252, v253
	v_cvt_pk_bf16_f32 v106, v248, v249
	v_cvt_pk_bf16_f32 v98, v146, v147
	v_mfma_f32_32x32x16_bf16 v[48:63], v[182:185], v[80:83], v[48:63]
	v_exp_f32_e32 v251, v251
	v_exp_f32_e32 v149, v149
	v_add_f32_e32 v253, v250, v148
	v_add_f32_e32 v252, v252, v253
	v_add_f32_e32 v253, v251, v149
	v_add_f32_e32 v252, v252, v253
	v_cvt_pk_bf16_f32 v107, v250, v251
	v_cvt_pk_bf16_f32 v99, v148, v149
	v_add_f32_e32 v131, v131, v252

.Lmb1_A_near:
	s_add_i32 s45, s37, 1
	s_cmp_ge_u32 s45, s30
	s_cbranch_scc1 .Lmb1_skKAn
	s_add_i32 s45, s44, 0x2000
	s_and_b32 s45, s45, 0x6000
	s_add_i32 s45, s45, s74
	s_mov_b32 s99, m0
	s_mov_b32 m0, s45
	s_nop 0
	global_load_lds_dwordx4 v[114:115], off
	s_mov_b32 m0, s99
	s_mov_b32 s43, 1
.Lmb1_skKAn:
	s_add_i32 s45, s37, 4
	s_cmp_ge_u32 s45, s35
	s_cbranch_scc1 .Lmb1_skVAn
	s_and_b32 s45, s44, 0x6000
	s_add_i32 s45, s45, s75
	s_mov_b32 s99, m0
	s_mov_b32 m0, s45
	s_nop 0
	global_load_lds_dwordx4 v[116:117], off
	s_mov_b32 m0, s99
	s_add_i32 s43, s43, 1
.Lmb1_skVAn:
	s_waitcnt lgkmcnt(8)
	v_mfma_f32_32x32x16_bf16 v[16:31], v[108:111], v[186:189], v[16:31]
	v_mfma_f32_32x32x16_bf16 v[16:31], v[104:107], v[190:193], v[16:31]
	v_mfma_f32_32x32x16_bf16 v[16:31], v[100:103], v[194:197], v[16:31]
	v_mfma_f32_32x32x16_bf16 v[16:31], v[96:99], v[198:201], v[16:31]
	v_mfma_f32_32x32x16_bf16 v[32:47], v[108:111], v[202:205], v[32:47]
	v_mfma_f32_32x32x16_bf16 v[32:47], v[104:107], v[206:209], v[32:47]
	v_mfma_f32_32x32x16_bf16 v[32:47], v[100:103], v[210:213], v[32:47]
	v_mfma_f32_32x32x16_bf16 v[32:47], v[96:99], v[214:217], v[32:47]
	s_lshr_b32 s44, s34, 2
	s_cmp_eq_u32 s44, s91
	s_cselect_b64 s[8:9], -1, 0
	s_lshl_b32 s44, 1, s44
	v_and_b32_e32 v96, s44, v129
	v_cmp_ne_u32_e32 vcc, 0, v96
	s_or_b64 vcc, s[8:9], vcc
	s_nop 0
	v_cndmask_b32_e32 v96, v127, v112, vcc
	v_lshl_add_u32 v96, v96, 2, 0
	v_add_u32_e32 v104, 0x1d000, v96
	ds_read2_b32 v[96:97], v104 offset0:58 offset1:59
	ds_read2_b32 v[98:99], v104 offset0:26 offset1:27
	ds_read2_b32 v[100:101], v104 offset0:56 offset1:57
	s_waitcnt lgkmcnt(2)
	v_pk_add_f32 v[64:65], v[64:65], v[96:97] op_sel:[0,1] op_sel_hi:[1,0]
	ds_read2_b32 v[96:97], v104 offset0:24 offset1:25
	s_waitcnt lgkmcnt(2)
	v_pk_add_f32 v[48:49], v[48:49], v[98:99] op_sel:[0,1] op_sel_hi:[1,0]
	ds_read2_b32 v[98:99], v104 offset0:50 offset1:51
	s_waitcnt lgkmcnt(2)
	v_pk_add_f32 v[66:67], v[66:67], v[100:101] op_sel:[0,1] op_sel_hi:[1,0]
	ds_read2_b32 v[100:101], v104 offset0:18 offset1:19
	s_waitcnt lgkmcnt(1)
	v_pk_add_f32 v[68:69], v[68:69], v[98:99] op_sel:[0,1] op_sel_hi:[1,0]
	ds_read2_b32 v[98:99], v104 offset0:16 offset1:17
	s_waitcnt lgkmcnt(1)
	v_pk_add_f32 v[52:53], v[52:53], v[100:101] op_sel:[0,1] op_sel_hi:[1,0]
	ds_read2_b32 v[100:101], v104 offset0:42 offset1:43
	v_pk_add_f32 v[50:51], v[50:51], v[96:97] op_sel:[0,1] op_sel_hi:[1,0]
	ds_read2_b32 v[96:97], v104 offset0:48 offset1:49
	s_waitcnt lgkmcnt(1)
	v_pk_add_f32 v[72:73], v[72:73], v[100:101] op_sel:[0,1] op_sel_hi:[1,0]
	ds_read2_b32 v[100:101], v104 offset0:8 offset1:9
	s_waitcnt lgkmcnt(1)
	v_pk_add_f32 v[70:71], v[70:71], v[96:97] op_sel:[0,1] op_sel_hi:[1,0]
	ds_read2_b32 v[96:97], v104 offset0:10 offset1:11
	v_pk_add_f32 v[54:55], v[54:55], v[98:99] op_sel:[0,1] op_sel_hi:[1,0]
	ds_read2_b32 v[98:99], v104 offset0:40 offset1:41
	s_waitcnt lgkmcnt(2)
	v_pk_add_f32 v[58:59], v[58:59], v[100:101] op_sel:[0,1] op_sel_hi:[1,0]
	s_waitcnt lgkmcnt(1)
	v_pk_add_f32 v[56:57], v[56:57], v[96:97] op_sel:[0,1] op_sel_hi:[1,0]
	ds_read2_b32 v[96:97], v104 offset0:34 offset1:35
	s_waitcnt lgkmcnt(1)
	v_pk_add_f32 v[74:75], v[74:75], v[98:99] op_sel:[0,1] op_sel_hi:[1,0]
	ds_read2_b32 v[98:99], v104 offset0:2 offset1:3
	ds_read2_b32 v[102:103], v104 offset0:32 offset1:33
	ds_read2_b32 v[104:105], v104 offset1:1
	s_waitcnt lgkmcnt(3)
	v_pk_add_f32 v[76:77], v[76:77], v[96:97] op_sel:[0,1] op_sel_hi:[1,0]
	s_waitcnt lgkmcnt(2)
	v_pk_add_f32 v[60:61], v[60:61], v[98:99] op_sel:[0,1] op_sel_hi:[1,0]
	s_waitcnt lgkmcnt(1)
	v_pk_add_f32 v[78:79], v[78:79], v[102:103] op_sel:[0,1] op_sel_hi:[1,0]
	s_waitcnt lgkmcnt(0)
	v_pk_add_f32 v[62:63], v[62:63], v[104:105] op_sel:[0,1] op_sel_hi:[1,0]
	s_waitcnt lgkmcnt(0)
	v_mfma_f32_32x32x16_bf16 v[236:251], v[154:157], v[92:95], v[220:235]
	ds_read_b64_tr_b16 v[186:187], v218
	ds_read_b64_tr_b16 v[188:189], v218 offset:512
	ds_read_b64_tr_b16 v[190:191], v218 offset:1024
	ds_read_b64_tr_b16 v[192:193], v218 offset:1536
	ds_read_b64_tr_b16 v[194:195], v218 offset:2048
	ds_read_b64_tr_b16 v[196:197], v218 offset:2560
	ds_read_b64_tr_b16 v[198:199], v218 offset:3072
	ds_read_b64_tr_b16 v[200:201], v218 offset:3584
	ds_read_b64_tr_b16 v[202:203], v218 offset:4096
	ds_read_b64_tr_b16 v[204:205], v218 offset:4608
	ds_read_b64_tr_b16 v[206:207], v218 offset:5120
	v_mfma_f32_32x32x16_bf16 v[134:149], v[158:161], v[92:95], v[220:235]
	ds_read_b64_tr_b16 v[208:209], v218 offset:5632
	ds_read_b64_tr_b16 v[210:211], v218 offset:6144
	ds_read_b64_tr_b16 v[212:213], v218 offset:6656
	ds_read_b64_tr_b16 v[214:215], v218 offset:7168
	ds_read_b64_tr_b16 v[216:217], v218 offset:7680
	v_exp_f32_e32 v64, v64
	v_exp_f32_e32 v48, v48
	v_exp_f32_e32 v65, v65
	v_exp_f32_e32 v49, v49
	v_exp_f32_e32 v66, v66
	v_exp_f32_e32 v50, v50
	v_mfma_f32_32x32x16_bf16 v[236:251], v[162:165], v[88:91], v[236:251]
	v_exp_f32_e32 v67, v67
	v_exp_f32_e32 v51, v51
	v_add_f32_e32 v252, v48, v64
	v_exp_f32_e32 v68, v68
	v_exp_f32_e32 v52, v52
	v_add_f32_e32 v252, 0, v252
	v_add_f32_e32 v253, v49, v65
	v_exp_f32_e32 v69, v69
	v_exp_f32_e32 v53, v53
	v_add_f32_e32 v252, v253, v252
	v_add_f32_e32 v253, v50, v66
	v_mfma_f32_32x32x16_bf16 v[134:149], v[166:169], v[88:91], v[134:149]
	v_exp_f32_e32 v70, v70
	v_exp_f32_e32 v54, v54
	v_add_f32_e32 v252, v253, v252
	v_add_f32_e32 v253, v51, v67
	v_exp_f32_e32 v71, v71
	v_exp_f32_e32 v55, v55
	v_add_f32_e32 v252, v253, v252
	v_add_f32_e32 v253, v52, v68
	v_exp_f32_e32 v72, v72
	v_exp_f32_e32 v56, v56
	v_add_f32_e32 v252, v253, v252
	v_mfma_f32_32x32x16_bf16 v[236:251], v[170:173], v[84:87], v[236:251]
	v_add_f32_e32 v253, v53, v69
	v_exp_f32_e32 v73, v73
	v_exp_f32_e32 v57, v57
	v_add_f32_e32 v252, v253, v252
	v_add_f32_e32 v253, v54, v70
	v_exp_f32_e32 v74, v74
	v_exp_f32_e32 v58, v58
	v_add_f32_e32 v252, v253, v252
	v_add_f32_e32 v253, v55, v71
	v_exp_f32_e32 v75, v75
	v_exp_f32_e32 v59, v59
	v_mfma_f32_32x32x16_bf16 v[134:149], v[174:177], v[84:87], v[134:149]
	v_add_f32_e32 v252, v253, v252
	v_add_f32_e32 v253, v56, v72
	v_exp_f32_e32 v76, v76
	v_exp_f32_e32 v60, v60
	v_add_f32_e32 v252, v253, v252
	v_add_f32_e32 v253, v57, v73
	v_exp_f32_e32 v77, v77
	v_exp_f32_e32 v61, v61
	v_add_f32_e32 v252, v253, v252
	v_add_f32_e32 v253, v58, v74
	v_exp_f32_e32 v78, v78
	v_mfma_f32_32x32x16_bf16 v[236:251], v[178:181], v[80:83], v[236:251]
	v_exp_f32_e32 v62, v62
	v_add_f32_e32 v252, v253, v252
	v_add_f32_e32 v253, v59, v75
	v_exp_f32_e32 v79, v79
	v_exp_f32_e32 v63, v63
	v_add_f32_e32 v252, v253, v252
	v_add_f32_e32 v253, v60, v76
	v_add_f32_e32 v252, v253, v252
	v_add_f32_e32 v253, v61, v77
	v_add_f32_e32 v252, v253, v252
	v_add_f32_e32 v253, v62, v78
	v_mfma_f32_32x32x16_bf16 v[134:149], v[182:185], v[80:83], v[134:149]
	v_add_f32_e32 v252, v253, v252
	v_add_f32_e32 v253, v63, v79
	v_add_f32_e32 v252, v253, v252
	v_add_f32_e32 v131, v131, v252
	v_cvt_pk_bf16_f32 v108, v64, v65
	v_cvt_pk_bf16_f32 v109, v66, v67
	v_cvt_pk_bf16_f32 v110, v68, v69
	v_cvt_pk_bf16_f32 v111, v70, v71
	v_cvt_pk_bf16_f32 v104, v72, v73
	v_cvt_pk_bf16_f32 v105, v74, v75
	v_cvt_pk_bf16_f32 v106, v76, v77
	v_cvt_pk_bf16_f32 v107, v78, v79
	v_cvt_pk_bf16_f32 v100, v48, v49
	v_cvt_pk_bf16_f32 v101, v50, v51
	v_cvt_pk_bf16_f32 v102, v52, v53
	v_cvt_pk_bf16_f32 v103, v54, v55
	v_cvt_pk_bf16_f32 v96, v56, v57
	v_cvt_pk_bf16_f32 v97, v58, v59
	v_cvt_pk_bf16_f32 v98, v60, v61
	v_cvt_pk_bf16_f32 v99, v62, v63
	s_branch .Lmb1_A_tail

.Lmb1_skKBn:
	s_add_i32 s45, s37, 4
	s_cmp_ge_u32 s45, s35
	s_cbranch_scc1 .Lmb1_skVBn
	s_and_b32 s45, s44, 0x6000
	s_add_i32 s45, s45, s75
	s_mov_b32 s99, m0
	s_mov_b32 m0, s45
	s_nop 0
	global_load_lds_dwordx4 v[116:117], off
	s_mov_b32 m0, s99
	s_add_i32 s43, s43, 1
.Lmb1_skVBn:
	s_waitcnt lgkmcnt(8)
	v_mfma_f32_32x32x16_bf16 v[16:31], v[108:111], v[186:189], v[16:31]
	v_mfma_f32_32x32x16_bf16 v[16:31], v[104:107], v[190:193], v[16:31]
	v_mfma_f32_32x32x16_bf16 v[16:31], v[100:103], v[194:197], v[16:31]
	v_mfma_f32_32x32x16_bf16 v[16:31], v[96:99], v[198:201], v[16:31]
	v_mfma_f32_32x32x16_bf16 v[32:47], v[108:111], v[202:205], v[32:47]
	v_mfma_f32_32x32x16_bf16 v[32:47], v[104:107], v[206:209], v[32:47]
	v_mfma_f32_32x32x16_bf16 v[32:47], v[100:103], v[210:213], v[32:47]
	v_mfma_f32_32x32x16_bf16 v[32:47], v[96:99], v[214:217], v[32:47]
	s_lshr_b32 s44, s34, 2
	s_cmp_eq_u32 s44, s91
	s_cselect_b64 s[8:9], -1, 0
	s_lshl_b32 s44, 1, s44
	v_and_b32_e32 v96, s44, v129
	v_cmp_ne_u32_e32 vcc, 0, v96
	s_or_b64 vcc, s[8:9], vcc
	s_nop 0
	v_cndmask_b32_e32 v96, v127, v112, vcc
	v_lshl_add_u32 v96, v96, 2, 0
	v_add_u32_e32 v104, 0x1d000, v96
	ds_read2_b32 v[96:97], v104 offset0:58 offset1:59
	ds_read2_b32 v[98:99], v104 offset0:26 offset1:27
	ds_read2_b32 v[100:101], v104 offset0:56 offset1:57
	s_waitcnt lgkmcnt(2)
	v_pk_add_f32 v[236:237], v[236:237], v[96:97] op_sel:[0,1] op_sel_hi:[1,0]
	ds_read2_b32 v[96:97], v104 offset0:24 offset1:25
	s_waitcnt lgkmcnt(2)
	v_pk_add_f32 v[134:135], v[134:135], v[98:99] op_sel:[0,1] op_sel_hi:[1,0]
	ds_read2_b32 v[98:99], v104 offset0:50 offset1:51
	s_waitcnt lgkmcnt(2)
	v_pk_add_f32 v[238:239], v[238:239], v[100:101] op_sel:[0,1] op_sel_hi:[1,0]
	ds_read2_b32 v[100:101], v104 offset0:18 offset1:19
	s_waitcnt lgkmcnt(1)
	v_pk_add_f32 v[240:241], v[240:241], v[98:99] op_sel:[0,1] op_sel_hi:[1,0]
	ds_read2_b32 v[98:99], v104 offset0:16 offset1:17
	s_waitcnt lgkmcnt(1)
	v_pk_add_f32 v[138:139], v[138:139], v[100:101] op_sel:[0,1] op_sel_hi:[1,0]
	ds_read2_b32 v[100:101], v104 offset0:42 offset1:43
	v_pk_add_f32 v[136:137], v[136:137], v[96:97] op_sel:[0,1] op_sel_hi:[1,0]
	ds_read2_b32 v[96:97], v104 offset0:48 offset1:49
	s_waitcnt lgkmcnt(1)
	v_pk_add_f32 v[244:245], v[244:245], v[100:101] op_sel:[0,1] op_sel_hi:[1,0]
	ds_read2_b32 v[100:101], v104 offset0:8 offset1:9
	s_waitcnt lgkmcnt(1)
	v_pk_add_f32 v[242:243], v[242:243], v[96:97] op_sel:[0,1] op_sel_hi:[1,0]
	ds_read2_b32 v[96:97], v104 offset0:10 offset1:11
	v_pk_add_f32 v[140:141], v[140:141], v[98:99] op_sel:[0,1] op_sel_hi:[1,0]
	ds_read2_b32 v[98:99], v104 offset0:40 offset1:41
	s_waitcnt lgkmcnt(2)
	v_pk_add_f32 v[144:145], v[144:145], v[100:101] op_sel:[0,1] op_sel_hi:[1,0]
	s_waitcnt lgkmcnt(1)
	v_pk_add_f32 v[142:143], v[142:143], v[96:97] op_sel:[0,1] op_sel_hi:[1,0]
	ds_read2_b32 v[96:97], v104 offset0:34 offset1:35
	s_waitcnt lgkmcnt(1)
	v_pk_add_f32 v[246:247], v[246:247], v[98:99] op_sel:[0,1] op_sel_hi:[1,0]
	ds_read2_b32 v[98:99], v104 offset0:2 offset1:3
	ds_read2_b32 v[102:103], v104 offset0:32 offset1:33
	ds_read2_b32 v[104:105], v104 offset1:1
	s_waitcnt lgkmcnt(3)
	v_pk_add_f32 v[248:249], v[248:249], v[96:97] op_sel:[0,1] op_sel_hi:[1,0]
	s_waitcnt lgkmcnt(2)
	v_pk_add_f32 v[146:147], v[146:147], v[98:99] op_sel:[0,1] op_sel_hi:[1,0]
	s_waitcnt lgkmcnt(1)
	v_pk_add_f32 v[250:251], v[250:251], v[102:103] op_sel:[0,1] op_sel_hi:[1,0]
	s_waitcnt lgkmcnt(0)
	v_pk_add_f32 v[148:149], v[148:149], v[104:105] op_sel:[0,1] op_sel_hi:[1,0]
	s_waitcnt lgkmcnt(0)
	v_mfma_f32_32x32x16_bf16 v[64:79], v[154:157], v[92:95], v[220:235]
	ds_read_b64_tr_b16 v[186:187], v218
	ds_read_b64_tr_b16 v[188:189], v218 offset:512
	ds_read_b64_tr_b16 v[190:191], v218 offset:1024
	ds_read_b64_tr_b16 v[192:193], v218 offset:1536
	ds_read_b64_tr_b16 v[194:195], v218 offset:2048
	ds_read_b64_tr_b16 v[196:197], v218 offset:2560
	ds_read_b64_tr_b16 v[198:199], v218 offset:3072
	ds_read_b64_tr_b16 v[200:201], v218 offset:3584
	ds_read_b64_tr_b16 v[202:203], v218 offset:4096
	ds_read_b64_tr_b16 v[204:205], v218 offset:4608
	ds_read_b64_tr_b16 v[206:207], v218 offset:5120
	v_mfma_f32_32x32x16_bf16 v[48:63], v[158:161], v[92:95], v[220:235]
	ds_read_b64_tr_b16 v[208:209], v218 offset:5632
	ds_read_b64_tr_b16 v[210:211], v218 offset:6144
	ds_read_b64_tr_b16 v[212:213], v218 offset:6656
	ds_read_b64_tr_b16 v[214:215], v218 offset:7168
	ds_read_b64_tr_b16 v[216:217], v218 offset:7680
	v_exp_f32_e32 v236, v236
	v_exp_f32_e32 v134, v134
	v_exp_f32_e32 v237, v237
	v_exp_f32_e32 v135, v135
	v_exp_f32_e32 v238, v238
	v_exp_f32_e32 v136, v136
	v_mfma_f32_32x32x16_bf16 v[64:79], v[162:165], v[88:91], v[64:79]
	v_exp_f32_e32 v239, v239
	v_exp_f32_e32 v137, v137
	v_add_f32_e32 v252, v134, v236
	v_exp_f32_e32 v240, v240
	v_exp_f32_e32 v138, v138
	v_add_f32_e32 v252, 0, v252
	v_add_f32_e32 v253, v135, v237
	v_exp_f32_e32 v241, v241
	v_exp_f32_e32 v139, v139
	v_add_f32_e32 v252, v253, v252
	v_add_f32_e32 v253, v136, v238
	v_mfma_f32_32x32x16_bf16 v[48:63], v[166:169], v[88:91], v[48:63]
	v_exp_f32_e32 v242, v242
	v_exp_f32_e32 v140, v140
	v_add_f32_e32 v252, v253, v252
	v_add_f32_e32 v253, v137, v239
	v_exp_f32_e32 v243, v243
	v_exp_f32_e32 v141, v141
	v_add_f32_e32 v252, v253, v252
	v_add_f32_e32 v253, v138, v240
	v_exp_f32_e32 v244, v244
	v_exp_f32_e32 v142, v142
	v_add_f32_e32 v252, v253, v252
	v_mfma_f32_32x32x16_bf16 v[64:79], v[170:173], v[84:87], v[64:79]
	v_add_f32_e32 v253, v139, v241
	v_exp_f32_e32 v245, v245
	v_exp_f32_e32 v143, v143
	v_add_f32_e32 v252, v253, v252
	v_add_f32_e32 v253, v140, v242
	v_exp_f32_e32 v246, v246
	v_exp_f32_e32 v144, v144
	v_add_f32_e32 v252, v253, v252
	v_add_f32_e32 v253, v141, v243
	v_exp_f32_e32 v247, v247
	v_exp_f32_e32 v145, v145
	v_mfma_f32_32x32x16_bf16 v[48:63], v[174:177], v[84:87], v[48:63]
	v_add_f32_e32 v252, v253, v252
	v_add_f32_e32 v253, v142, v244
	v_exp_f32_e32 v248, v248
	v_exp_f32_e32 v146, v146
	v_add_f32_e32 v252, v253, v252
	v_add_f32_e32 v253, v143, v245
	v_exp_f32_e32 v249, v249
	v_exp_f32_e32 v147, v147
	v_add_f32_e32 v252, v253, v252
	v_add_f32_e32 v253, v144, v246
	v_exp_f32_e32 v250, v250
	v_mfma_f32_32x32x16_bf16 v[64:79], v[178:181], v[80:83], v[64:79]
	v_exp_f32_e32 v148, v148
	v_add_f32_e32 v252, v253, v252
	v_add_f32_e32 v253, v145, v247
	v_exp_f32_e32 v251, v251
	v_exp_f32_e32 v149, v149
	v_add_f32_e32 v252, v253, v252
	v_add_f32_e32 v253, v146, v248
	v_add_f32_e32 v252, v253, v252
	v_add_f32_e32 v253, v147, v249
	v_add_f32_e32 v252, v253, v252
	v_add_f32_e32 v253, v148, v250
	v_mfma_f32_32x32x16_bf16 v[48:63], v[182:185], v[80:83], v[48:63]
	v_add_f32_e32 v252, v253, v252
	v_add_f32_e32 v253, v149, v251
	v_add_f32_e32 v252, v253, v252
	v_add_f32_e32 v131, v131, v252
	v_cvt_pk_bf16_f32 v108, v236, v237
	v_cvt_pk_bf16_f32 v109, v238, v239
	v_cvt_pk_bf16_f32 v110, v240, v241
	v_cvt_pk_bf16_f32 v111, v242, v243
	v_cvt_pk_bf16_f32 v104, v244, v245
	v_cvt_pk_bf16_f32 v105, v246, v247
	v_cvt_pk_bf16_f32 v106, v248, v249
	v_cvt_pk_bf16_f32 v107, v250, v251
	v_cvt_pk_bf16_f32 v100, v134, v135
	v_cvt_pk_bf16_f32 v101, v136, v137
	v_cvt_pk_bf16_f32 v102, v138, v139
	v_cvt_pk_bf16_f32 v103, v140, v141
	v_cvt_pk_bf16_f32 v96, v142, v143
	v_cvt_pk_bf16_f32 v97, v144, v145
	v_cvt_pk_bf16_f32 v98, v146, v147
	v_cvt_pk_bf16_f32 v99, v148, v149
	s_branch .Lmb1_B_tail

; __device__ __forceinline__ void pv(f32x16* o, int vb, bf16x8 pa0, bf16x8 pa1, bf16x8 pa2, bf16x8 pa3) {
; #pragma unroll
;     for (int d0 = 0; d0 < 2; ++d0) { s16x4 lo[4], hi[4];
; #pragma unroll
;         for (int ks = 0; ks < 4; ++ks) {
;             asm volatile("ds_read_b64_tr_b16 %0,%1 offset:%c2" : "=&v"(lo[ks]) : "v"(vb), "i"(d0 * 4096 + ks * 1024) : "memory");
;             asm volatile("ds_read_b64_tr_b16 %0,%1 offset:%c2" : "=&v"(hi[ks]) : "v"(vb), "i"(d0 * 4096 + ks * 1024 + 512) : "memory"); }
;         asm volatile("s_waitcnt lgkmcnt(0)" ::: "memory"); __builtin_amdgcn_sched_barrier(0);
.LBB0_2383:
.LBB0_2384:
.LBB0_2386:
.Lmb3_A:
	s_barrier
	s_add_i32 s36, s43, 0x2000
	s_add_i32 s98, s43, 0x4000
	s_and_b32 s42, s98, 0x6000
	v_add_u32_e32 v133, s42, v130
	ds_read_b128 v[154:157], v133
	ds_read_b128 v[158:161], v133 offset:512
	ds_read_b128 v[162:165], v133 offset:2048
	ds_read_b128 v[166:169], v133 offset:2560
	ds_read_b128 v[170:173], v133 offset:4096
	ds_read_b128 v[174:177], v133 offset:4608
	ds_read_b128 v[178:181], v133 offset:6144
	ds_read_b128 v[182:185], v133 offset:6656
	s_and_b32 s42, s36, 0x6000
	v_add_u32_e32 v218, s42, v132
	s_add_i32 s98, s30, 2
	s_cmp_ge_i32 s30, s29
	s_cbranch_scc1 .Lmb3_A_near
	v_mfma_f32_32x32x16_bf16 v[16:31], v[108:111], v[186:189], v[16:31]
	v_exp_f32_e32 v64, v64
	v_exp_f32_e32 v48, v48
	v_mfma_f32_32x32x16_bf16 v[16:31], v[104:107], v[190:193], v[16:31]
	v_exp_f32_e32 v65, v65
	v_exp_f32_e32 v49, v49
	v_add_f32_e32 v252, v64, v48
	s_and_b64 vcc, exec, s[6:7]
	s_cbranch_vccz .Lmb3_A_g1skip
	s_add_i32 s42, s35, 1
	s_cmp_ge_u32 s42, s28
	s_cbranch_scc1 .Lmb3_skKAg
	s_add_i32 s42, s43, 0x2000
	s_and_b32 s42, s42, 0x6000
	s_add_i32 s42, s42, s74
	s_mov_b32 s99, m0
	s_mov_b32 m0, s42
	s_nop 0
	global_load_lds_dwordx4 v[114:115], off
	s_mov_b32 m0, s99
	s_mov_b32 s37, 1

; #define ATT_LAS __attribute__((address_space(3)))
; #define ATT_MFMA(a, b, c) __builtin_amdgcn_mfma_f32_32x32x16_bf16((a), (b), (c), 0, 0, 0)
; __device__ __forceinline__ void qkt(f32x16& p0, f32x16& p1, lds_cptr kb, const bf16x8* qr, const f32x16& z) {
; #pragma unroll
;     for (int d0 = 0; d0 < 4; ++d0) {
;         const bf16x8 b0 = *(const ATT_LAS bf16x8*)(kb + d0 * 2048);
;         const bf16x8 b1 = *(const ATT_LAS bf16x8*)(kb + d0 * 2048 + 512);
;         if (d0 == 0) { p0 = ATT_MFMA(b0, qr[0], z); p1 = ATT_MFMA(b1, qr[0], z); }
;         else { p0 = ATT_MFMA(b0, qr[d0], p0); p1 = ATT_MFMA(b1, qr[d0], p1); } }
; __device__ __forceinline__ void pv(f32x16* o, int vb, bf16x8 pa0, bf16x8 pa1, bf16x8 pa2, bf16x8 pa3) {
; #pragma unroll
;     for (int d0 = 0; d0 < 2; ++d0) { s16x4 lo[4], hi[4];
; #pragma unroll
;         for (int ks = 0; ks < 4; ++ks) {
;             asm volatile("ds_read_b64_tr_b16 %0,%1 offset:%c2" : "=&v"(lo[ks]) : "v"(vb), "i"(d0 * 4096 + ks * 1024) : "memory");
;             asm volatile("ds_read_b64_tr_b16 %0,%1 offset:%c2" : "=&v"(hi[ks]) : "v"(vb), "i"(d0 * 4096 + ks * 1024 + 512) : "memory"); }
;         asm volatile("s_waitcnt lgkmcnt(0)" ::: "memory"); __builtin_amdgcn_sched_barrier(0);
;     ...
;         o[d0] = ATT_MFMA(pa0, ATT_PK(0), o[d0]);
;         o[d0] = ATT_MFMA(pa1, ATT_PK(1), o[d0]);
;         o[d0] = ATT_MFMA(pa2, ATT_PK(2), o[d0]);
;         o[d0] = ATT_MFMA(pa3, ATT_PK(3), o[d0]);
;     ...
;     }
; }
.Lmb3_skVAg:
.Lmb3_A_g1skip:
	v_mfma_f32_32x32x16_bf16 v[16:31], v[100:103], v[194:197], v[16:31]
	v_exp_f32_e32 v66, v66
	v_exp_f32_e32 v50, v50
	v_add_f32_e32 v253, v65, v49
	v_add_f32_e32 v252, v252, v253
	v_mfma_f32_32x32x16_bf16 v[16:31], v[96:99], v[198:201], v[16:31]
	v_exp_f32_e32 v67, v67
	v_exp_f32_e32 v51, v51
	v_add_f32_e32 v253, v66, v50
	v_add_f32_e32 v252, v252, v253
	v_mfma_f32_32x32x16_bf16 v[32:47], v[108:111], v[202:205], v[32:47]
	v_exp_f32_e32 v68, v68
	v_exp_f32_e32 v52, v52
	v_add_f32_e32 v253, v67, v51
	v_add_f32_e32 v252, v252, v253
	ds_read_b64_tr_b16 v[186:187], v218
	ds_read_b64_tr_b16 v[188:189], v218 offset:512
	v_mfma_f32_32x32x16_bf16 v[32:47], v[104:107], v[206:209], v[32:47]
	v_exp_f32_e32 v69, v69
	v_exp_f32_e32 v53, v53
	v_add_f32_e32 v253, v68, v52
	v_add_f32_e32 v252, v252, v253
	ds_read_b64_tr_b16 v[190:191], v218 offset:1024
	ds_read_b64_tr_b16 v[192:193], v218 offset:1536
	v_mfma_f32_32x32x16_bf16 v[32:47], v[100:103], v[210:213], v[32:47]
	v_exp_f32_e32 v70, v70
	v_exp_f32_e32 v54, v54
	v_add_f32_e32 v253, v69, v53
	v_add_f32_e32 v252, v252, v253
	ds_read_b64_tr_b16 v[194:195], v218 offset:2048
	ds_read_b64_tr_b16 v[196:197], v218 offset:2560
	v_mfma_f32_32x32x16_bf16 v[32:47], v[96:99], v[214:217], v[32:47]
	v_exp_f32_e32 v71, v71
	v_exp_f32_e32 v55, v55
	v_add_f32_e32 v253, v70, v54
	v_add_f32_e32 v252, v252, v253
	ds_read_b64_tr_b16 v[198:199], v218 offset:3072
	ds_read_b64_tr_b16 v[200:201], v218 offset:3584
	s_waitcnt lgkmcnt(8)
	v_mfma_f32_32x32x16_bf16 v[236:251], v[154:157], v[92:95], v[220:235]
	v_exp_f32_e32 v72, v72
	v_exp_f32_e32 v56, v56
	v_add_f32_e32 v253, v71, v55
	v_add_f32_e32 v252, v252, v253
	v_cvt_pk_bf16_f32 v108, v64, v65
	v_cvt_pk_bf16_f32 v100, v48, v49
	ds_read_b64_tr_b16 v[202:203], v218 offset:4096
	ds_read_b64_tr_b16 v[204:205], v218 offset:4608
	v_mfma_f32_32x32x16_bf16 v[134:149], v[158:161], v[92:95], v[220:235]
	v_exp_f32_e32 v73, v73
	v_exp_f32_e32 v57, v57
	v_add_f32_e32 v253, v72, v56
	v_add_f32_e32 v252, v252, v253
	v_cvt_pk_bf16_f32 v109, v66, v67
	v_cvt_pk_bf16_f32 v101, v50, v51
	ds_read_b64_tr_b16 v[206:207], v218 offset:5120
	ds_read_b64_tr_b16 v[208:209], v218 offset:5632
	s_and_b64 vcc, exec, s[6:7]
	s_cbranch_vccnz .Lmb3_A_g0mid
	s_add_i32 s42, s35, 1
	s_cmp_ge_u32 s42, s28
	s_cbranch_scc1 .Lmb3_skKAm
	s_add_i32 s42, s43, 0x2000
	s_and_b32 s42, s42, 0x6000
	s_add_i32 s42, s42, s74
	s_mov_b32 s99, m0
	s_mov_b32 m0, s42
	s_nop 0
	global_load_lds_dwordx4 v[114:115], off
	s_mov_b32 m0, s99
	s_mov_b32 s37, 1

; __device__ __forceinline__ void pv(f32x16* o, int vb, bf16x8 pa0, bf16x8 pa1, bf16x8 pa2, bf16x8 pa3) {
; #pragma unroll
;     for (int d0 = 0; d0 < 2; ++d0) { s16x4 lo[4], hi[4];
; #pragma unroll
;         for (int ks = 0; ks < 4; ++ks) {
;             asm volatile("ds_read_b64_tr_b16 %0,%1 offset:%c2" : "=&v"(lo[ks]) : "v"(vb), "i"(d0 * 4096 + ks * 1024) : "memory");
;             asm volatile("ds_read_b64_tr_b16 %0,%1 offset:%c2" : "=&v"(hi[ks]) : "v"(vb), "i"(d0 * 4096 + ks * 1024 + 512) : "memory"); }
;         asm volatile("s_waitcnt lgkmcnt(0)" ::: "memory"); __builtin_amdgcn_sched_barrier(0);
.Lmb3_B:
	s_barrier
	s_add_i32 s36, s43, 0x2000
	s_add_i32 s98, s43, 0x4000
	s_and_b32 s42, s98, 0x6000
	v_add_u32_e32 v133, s42, v130
	ds_read_b128 v[154:157], v133
	ds_read_b128 v[158:161], v133 offset:512
	ds_read_b128 v[162:165], v133 offset:2048
	ds_read_b128 v[166:169], v133 offset:2560
	ds_read_b128 v[170:173], v133 offset:4096
	ds_read_b128 v[174:177], v133 offset:4608
	ds_read_b128 v[178:181], v133 offset:6144
	ds_read_b128 v[182:185], v133 offset:6656
	s_and_b32 s42, s36, 0x6000
	v_add_u32_e32 v218, s42, v132
	s_add_i32 s98, s30, 2
	s_cmp_ge_i32 s30, s29
	s_cbranch_scc1 .Lmb3_B_near
	v_mfma_f32_32x32x16_bf16 v[16:31], v[108:111], v[186:189], v[16:31]
	v_exp_f32_e32 v236, v236
	v_exp_f32_e32 v134, v134
	v_mfma_f32_32x32x16_bf16 v[16:31], v[104:107], v[190:193], v[16:31]
	v_exp_f32_e32 v237, v237
	v_exp_f32_e32 v135, v135
	v_add_f32_e32 v252, v236, v134
	s_and_b64 vcc, exec, s[6:7]
	s_cbranch_vccz .Lmb3_B_g1skip
	s_add_i32 s42, s35, 1
	s_cmp_ge_u32 s42, s28
	s_cbranch_scc1 .Lmb3_skKBg
	s_add_i32 s42, s43, 0x2000
	s_and_b32 s42, s42, 0x6000
	s_add_i32 s42, s42, s74
	s_mov_b32 s99, m0
	s_mov_b32 m0, s42
	s_nop 0
	global_load_lds_dwordx4 v[114:115], off
	s_mov_b32 m0, s99
	s_mov_b32 s37, 1

; #define ATT_LAS __attribute__((address_space(3)))
; #define ATT_MFMA(a, b, c) __builtin_amdgcn_mfma_f32_32x32x16_bf16((a), (b), (c), 0, 0, 0)
; __device__ __forceinline__ void qkt(f32x16& p0, f32x16& p1, lds_cptr kb, const bf16x8* qr, const f32x16& z) {
; #pragma unroll
;     for (int d0 = 0; d0 < 4; ++d0) {
;         const bf16x8 b0 = *(const ATT_LAS bf16x8*)(kb + d0 * 2048);
;         const bf16x8 b1 = *(const ATT_LAS bf16x8*)(kb + d0 * 2048 + 512);
;         if (d0 == 0) { p0 = ATT_MFMA(b0, qr[0], z); p1 = ATT_MFMA(b1, qr[0], z); }
;         else { p0 = ATT_MFMA(b0, qr[d0], p0); p1 = ATT_MFMA(b1, qr[d0], p1); } }
; __device__ __forceinline__ void pv(f32x16* o, int vb, bf16x8 pa0, bf16x8 pa1, bf16x8 pa2, bf16x8 pa3) {
; #pragma unroll
;     for (int d0 = 0; d0 < 2; ++d0) { s16x4 lo[4], hi[4];
; #pragma unroll
;         for (int ks = 0; ks < 4; ++ks) {
;             asm volatile("ds_read_b64_tr_b16 %0,%1 offset:%c2" : "=&v"(lo[ks]) : "v"(vb), "i"(d0 * 4096 + ks * 1024) : "memory");
;             asm volatile("ds_read_b64_tr_b16 %0,%1 offset:%c2" : "=&v"(hi[ks]) : "v"(vb), "i"(d0 * 4096 + ks * 1024 + 512) : "memory"); }
;         asm volatile("s_waitcnt lgkmcnt(0)" ::: "memory"); __builtin_amdgcn_sched_barrier(0);
;     ...
;         o[d0] = ATT_MFMA(pa0, ATT_PK(0), o[d0]);
;         o[d0] = ATT_MFMA(pa1, ATT_PK(1), o[d0]);
;         o[d0] = ATT_MFMA(pa2, ATT_PK(2), o[d0]);
;         o[d0] = ATT_MFMA(pa3, ATT_PK(3), o[d0]);
;     ...
;     }
; }
.Lmb3_skVBg:
.Lmb3_B_g1skip:
	v_mfma_f32_32x32x16_bf16 v[16:31], v[100:103], v[194:197], v[16:31]
	v_exp_f32_e32 v238, v238
	v_exp_f32_e32 v136, v136
	v_add_f32_e32 v253, v237, v135
	v_add_f32_e32 v252, v252, v253
	v_mfma_f32_32x32x16_bf16 v[16:31], v[96:99], v[198:201], v[16:31]
	v_exp_f32_e32 v239, v239
	v_exp_f32_e32 v137, v137
	v_add_f32_e32 v253, v238, v136
	v_add_f32_e32 v252, v252, v253
	v_mfma_f32_32x32x16_bf16 v[32:47], v[108:111], v[202:205], v[32:47]
	v_exp_f32_e32 v240, v240
	v_exp_f32_e32 v138, v138
	v_add_f32_e32 v253, v239, v137
	v_add_f32_e32 v252, v252, v253
	ds_read_b64_tr_b16 v[186:187], v218
	ds_read_b64_tr_b16 v[188:189], v218 offset:512
	v_mfma_f32_32x32x16_bf16 v[32:47], v[104:107], v[206:209], v[32:47]
	v_exp_f32_e32 v241, v241
	v_exp_f32_e32 v139, v139
	v_add_f32_e32 v253, v240, v138
	v_add_f32_e32 v252, v252, v253
	ds_read_b64_tr_b16 v[190:191], v218 offset:1024
	ds_read_b64_tr_b16 v[192:193], v218 offset:1536
	v_mfma_f32_32x32x16_bf16 v[32:47], v[100:103], v[210:213], v[32:47]
	v_exp_f32_e32 v242, v242
	v_exp_f32_e32 v140, v140
	v_add_f32_e32 v253, v241, v139
	v_add_f32_e32 v252, v252, v253
	ds_read_b64_tr_b16 v[194:195], v218 offset:2048
	ds_read_b64_tr_b16 v[196:197], v218 offset:2560
	v_mfma_f32_32x32x16_bf16 v[32:47], v[96:99], v[214:217], v[32:47]
	v_exp_f32_e32 v243, v243
	v_exp_f32_e32 v141, v141
	v_add_f32_e32 v253, v242, v140
	v_add_f32_e32 v252, v252, v253
	ds_read_b64_tr_b16 v[198:199], v218 offset:3072
	ds_read_b64_tr_b16 v[200:201], v218 offset:3584
	s_waitcnt lgkmcnt(8)
	v_mfma_f32_32x32x16_bf16 v[64:79], v[154:157], v[92:95], v[220:235]
	v_exp_f32_e32 v244, v244
	v_exp_f32_e32 v142, v142
	v_add_f32_e32 v253, v243, v141
	v_add_f32_e32 v252, v252, v253
	v_cvt_pk_bf16_f32 v108, v236, v237
	v_cvt_pk_bf16_f32 v100, v134, v135
	ds_read_b64_tr_b16 v[202:203], v218 offset:4096
	ds_read_b64_tr_b16 v[204:205], v218 offset:4608
	v_mfma_f32_32x32x16_bf16 v[48:63], v[158:161], v[92:95], v[220:235]
	v_exp_f32_e32 v245, v245
	v_exp_f32_e32 v143, v143
	v_add_f32_e32 v253, v244, v142
	v_add_f32_e32 v252, v252, v253
	v_cvt_pk_bf16_f32 v109, v238, v239
	v_cvt_pk_bf16_f32 v101, v136, v137
	ds_read_b64_tr_b16 v[206:207], v218 offset:5120
	ds_read_b64_tr_b16 v[208:209], v218 offset:5632
	s_and_b64 vcc, exec, s[6:7]
	s_cbranch_vccnz .Lmb3_B_g0mid
	s_add_i32 s42, s35, 1
	s_cmp_ge_u32 s42, s28
	s_cbranch_scc1 .Lmb3_skKBm
	s_add_i32 s42, s43, 0x2000
	s_and_b32 s42, s42, 0x6000
	s_add_i32 s42, s42, s74
	s_mov_b32 s99, m0
	s_mov_b32 m0, s42
	s_nop 0
	global_load_lds_dwordx4 v[114:115], off
	s_mov_b32 m0, s99
	s_mov_b32 s37, 1

.Lmb3_A_near:
	s_add_i32 s42, s35, 1
	s_cmp_ge_u32 s42, s28
	s_cbranch_scc1 .Lmb3_skKAn
	s_add_i32 s42, s43, 0x2000
	s_and_b32 s42, s42, 0x6000
	s_add_i32 s42, s42, s74
	s_mov_b32 s99, m0
	s_mov_b32 m0, s42
	s_nop 0
	global_load_lds_dwordx4 v[114:115], off
	s_mov_b32 m0, s99
	s_mov_b32 s37, 1
.Lmb3_skKAn:
	s_add_i32 s42, s35, 4
	s_cmp_ge_u32 s42, s31
	s_cbranch_scc1 .Lmb3_skVAn
	s_and_b32 s42, s43, 0x6000
	s_add_i32 s42, s42, s75
	s_mov_b32 s99, m0
	s_mov_b32 m0, s42
	s_nop 0
	global_load_lds_dwordx4 v[116:117], off
	s_mov_b32 m0, s99
	s_add_i32 s37, s37, 1
.Lmb3_skVAn:
	s_waitcnt lgkmcnt(8)
	v_mfma_f32_32x32x16_bf16 v[16:31], v[108:111], v[186:189], v[16:31]
	v_mfma_f32_32x32x16_bf16 v[16:31], v[104:107], v[190:193], v[16:31]
	v_mfma_f32_32x32x16_bf16 v[16:31], v[100:103], v[194:197], v[16:31]
	v_mfma_f32_32x32x16_bf16 v[16:31], v[96:99], v[198:201], v[16:31]
	v_mfma_f32_32x32x16_bf16 v[32:47], v[108:111], v[202:205], v[32:47]
	v_mfma_f32_32x32x16_bf16 v[32:47], v[104:107], v[206:209], v[32:47]
	v_mfma_f32_32x32x16_bf16 v[32:47], v[100:103], v[210:213], v[32:47]
	v_mfma_f32_32x32x16_bf16 v[32:47], v[96:99], v[214:217], v[32:47]
	s_lshr_b32 s42, s30, 2
	s_cmp_eq_u32 s42, s93
	s_cselect_b64 s[10:11], -1, 0
	s_lshl_b32 s42, 1, s42
	v_and_b32_e32 v96, s42, v129
	v_cmp_ne_u32_e32 vcc, 0, v96
	s_or_b64 vcc, s[10:11], vcc
	s_nop 0
	v_cndmask_b32_e32 v96, v127, v112, vcc
	v_lshl_add_u32 v96, v96, 2, 0
	v_add_u32_e32 v104, 0x1d000, v96
	ds_read2_b32 v[96:97], v104 offset0:58 offset1:59
	ds_read2_b32 v[98:99], v104 offset0:26 offset1:27
	ds_read2_b32 v[100:101], v104 offset0:56 offset1:57
	s_waitcnt lgkmcnt(2)
	v_pk_add_f32 v[64:65], v[64:65], v[96:97] op_sel:[0,1] op_sel_hi:[1,0]
	ds_read2_b32 v[96:97], v104 offset0:24 offset1:25
	s_waitcnt lgkmcnt(2)
	v_pk_add_f32 v[48:49], v[48:49], v[98:99] op_sel:[0,1] op_sel_hi:[1,0]
	ds_read2_b32 v[98:99], v104 offset0:50 offset1:51
	s_waitcnt lgkmcnt(2)
	v_pk_add_f32 v[66:67], v[66:67], v[100:101] op_sel:[0,1] op_sel_hi:[1,0]
	ds_read2_b32 v[100:101], v104 offset0:18 offset1:19
	s_waitcnt lgkmcnt(1)
	v_pk_add_f32 v[68:69], v[68:69], v[98:99] op_sel:[0,1] op_sel_hi:[1,0]
	ds_read2_b32 v[98:99], v104 offset0:16 offset1:17
	s_waitcnt lgkmcnt(1)
	v_pk_add_f32 v[52:53], v[52:53], v[100:101] op_sel:[0,1] op_sel_hi:[1,0]
	ds_read2_b32 v[100:101], v104 offset0:42 offset1:43
	v_pk_add_f32 v[50:51], v[50:51], v[96:97] op_sel:[0,1] op_sel_hi:[1,0]
	ds_read2_b32 v[96:97], v104 offset0:48 offset1:49
	s_waitcnt lgkmcnt(1)
	v_pk_add_f32 v[72:73], v[72:73], v[100:101] op_sel:[0,1] op_sel_hi:[1,0]
	ds_read2_b32 v[100:101], v104 offset0:8 offset1:9
	s_waitcnt lgkmcnt(1)
	v_pk_add_f32 v[70:71], v[70:71], v[96:97] op_sel:[0,1] op_sel_hi:[1,0]
	ds_read2_b32 v[96:97], v104 offset0:10 offset1:11
	v_pk_add_f32 v[54:55], v[54:55], v[98:99] op_sel:[0,1] op_sel_hi:[1,0]
	ds_read2_b32 v[98:99], v104 offset0:40 offset1:41
	s_waitcnt lgkmcnt(2)
	v_pk_add_f32 v[58:59], v[58:59], v[100:101] op_sel:[0,1] op_sel_hi:[1,0]
	s_waitcnt lgkmcnt(1)
	v_pk_add_f32 v[56:57], v[56:57], v[96:97] op_sel:[0,1] op_sel_hi:[1,0]
	ds_read2_b32 v[96:97], v104 offset0:34 offset1:35
	s_waitcnt lgkmcnt(1)
	v_pk_add_f32 v[74:75], v[74:75], v[98:99] op_sel:[0,1] op_sel_hi:[1,0]
	ds_read2_b32 v[98:99], v104 offset0:2 offset1:3
	ds_read2_b32 v[102:103], v104 offset0:32 offset1:33
	ds_read2_b32 v[104:105], v104 offset1:1
	s_waitcnt lgkmcnt(3)
	v_pk_add_f32 v[76:77], v[76:77], v[96:97] op_sel:[0,1] op_sel_hi:[1,0]
	s_waitcnt lgkmcnt(2)
	v_pk_add_f32 v[60:61], v[60:61], v[98:99] op_sel:[0,1] op_sel_hi:[1,0]
	s_waitcnt lgkmcnt(1)
	v_pk_add_f32 v[78:79], v[78:79], v[102:103] op_sel:[0,1] op_sel_hi:[1,0]
	s_waitcnt lgkmcnt(0)
	v_pk_add_f32 v[62:63], v[62:63], v[104:105] op_sel:[0,1] op_sel_hi:[1,0]
	s_waitcnt lgkmcnt(0)
	v_mfma_f32_32x32x16_bf16 v[236:251], v[154:157], v[92:95], v[220:235]
	ds_read_b64_tr_b16 v[186:187], v218
	ds_read_b64_tr_b16 v[188:189], v218 offset:512
	ds_read_b64_tr_b16 v[190:191], v218 offset:1024
	ds_read_b64_tr_b16 v[192:193], v218 offset:1536
	ds_read_b64_tr_b16 v[194:195], v218 offset:2048
	ds_read_b64_tr_b16 v[196:197], v218 offset:2560
	ds_read_b64_tr_b16 v[198:199], v218 offset:3072
	ds_read_b64_tr_b16 v[200:201], v218 offset:3584
	ds_read_b64_tr_b16 v[202:203], v218 offset:4096
	ds_read_b64_tr_b16 v[204:205], v218 offset:4608
	ds_read_b64_tr_b16 v[206:207], v218 offset:5120
	v_mfma_f32_32x32x16_bf16 v[134:149], v[158:161], v[92:95], v[220:235]
	ds_read_b64_tr_b16 v[208:209], v218 offset:5632
	ds_read_b64_tr_b16 v[210:211], v218 offset:6144
	ds_read_b64_tr_b16 v[212:213], v218 offset:6656
	ds_read_b64_tr_b16 v[214:215], v218 offset:7168
	ds_read_b64_tr_b16 v[216:217], v218 offset:7680
	v_exp_f32_e32 v64, v64
	v_exp_f32_e32 v48, v48
	v_exp_f32_e32 v65, v65
	v_exp_f32_e32 v49, v49
	v_exp_f32_e32 v66, v66
	v_exp_f32_e32 v50, v50
	v_mfma_f32_32x32x16_bf16 v[236:251], v[162:165], v[88:91], v[236:251]
	v_exp_f32_e32 v67, v67
	v_exp_f32_e32 v51, v51
	v_add_f32_e32 v252, v48, v64
	v_exp_f32_e32 v68, v68
	v_exp_f32_e32 v52, v52
	v_add_f32_e32 v252, 0, v252
	v_add_f32_e32 v253, v49, v65
	v_exp_f32_e32 v69, v69
	v_exp_f32_e32 v53, v53
	v_add_f32_e32 v252, v253, v252
	v_add_f32_e32 v253, v50, v66
	v_mfma_f32_32x32x16_bf16 v[134:149], v[166:169], v[88:91], v[134:149]
	v_exp_f32_e32 v70, v70
	v_exp_f32_e32 v54, v54
	v_add_f32_e32 v252, v253, v252
	v_add_f32_e32 v253, v51, v67
	v_exp_f32_e32 v71, v71
	v_exp_f32_e32 v55, v55
	v_add_f32_e32 v252, v253, v252
	v_add_f32_e32 v253, v52, v68
	v_exp_f32_e32 v72, v72
	v_exp_f32_e32 v56, v56
	v_add_f32_e32 v252, v253, v252
	v_mfma_f32_32x32x16_bf16 v[236:251], v[170:173], v[84:87], v[236:251]
	v_add_f32_e32 v253, v53, v69
	v_exp_f32_e32 v73, v73
	v_exp_f32_e32 v57, v57
	v_add_f32_e32 v252, v253, v252
	v_add_f32_e32 v253, v54, v70
	v_exp_f32_e32 v74, v74
	v_exp_f32_e32 v58, v58
	v_add_f32_e32 v252, v253, v252
	v_add_f32_e32 v253, v55, v71
	v_exp_f32_e32 v75, v75
	v_exp_f32_e32 v59, v59
	v_mfma_f32_32x32x16_bf16 v[134:149], v[174:177], v[84:87], v[134:149]
	v_add_f32_e32 v252, v253, v252
	v_add_f32_e32 v253, v56, v72
	v_exp_f32_e32 v76, v76
	v_exp_f32_e32 v60, v60
	v_add_f32_e32 v252, v253, v252
	v_add_f32_e32 v253, v57, v73
	v_exp_f32_e32 v77, v77
	v_exp_f32_e32 v61, v61
	v_add_f32_e32 v252, v253, v252
	v_add_f32_e32 v253, v58, v74
	v_exp_f32_e32 v78, v78
	v_mfma_f32_32x32x16_bf16 v[236:251], v[178:181], v[80:83], v[236:251]
	v_exp_f32_e32 v62, v62
	v_add_f32_e32 v252, v253, v252
	v_add_f32_e32 v253, v59, v75
	v_exp_f32_e32 v79, v79
	v_exp_f32_e32 v63, v63
	v_add_f32_e32 v252, v253, v252
	v_add_f32_e32 v253, v60, v76
	v_add_f32_e32 v252, v253, v252
	v_add_f32_e32 v253, v61, v77
	v_add_f32_e32 v252, v253, v252
	v_add_f32_e32 v253, v62, v78
	v_mfma_f32_32x32x16_bf16 v[134:149], v[182:185], v[80:83], v[134:149]
	v_add_f32_e32 v252, v253, v252
	v_add_f32_e32 v253, v63, v79
	v_add_f32_e32 v252, v253, v252
	v_add_f32_e32 v131, v131, v252
	v_cvt_pk_bf16_f32 v108, v64, v65
	v_cvt_pk_bf16_f32 v109, v66, v67
	v_cvt_pk_bf16_f32 v110, v68, v69
	v_cvt_pk_bf16_f32 v111, v70, v71
	v_cvt_pk_bf16_f32 v104, v72, v73
	v_cvt_pk_bf16_f32 v105, v74, v75
	v_cvt_pk_bf16_f32 v106, v76, v77
	v_cvt_pk_bf16_f32 v107, v78, v79
	v_cvt_pk_bf16_f32 v100, v48, v49
	v_cvt_pk_bf16_f32 v101, v50, v51
	v_cvt_pk_bf16_f32 v102, v52, v53
	v_cvt_pk_bf16_f32 v103, v54, v55
	v_cvt_pk_bf16_f32 v96, v56, v57
	v_cvt_pk_bf16_f32 v97, v58, v59
	v_cvt_pk_bf16_f32 v98, v60, v61
	v_cvt_pk_bf16_f32 v99, v62, v63
	s_branch .Lmb3_A_tail

.Lmb3_skKBn:
	s_add_i32 s42, s35, 4
	s_cmp_ge_u32 s42, s31
	s_cbranch_scc1 .Lmb3_skVBn
	s_and_b32 s42, s43, 0x6000
	s_add_i32 s42, s42, s75
	s_mov_b32 s99, m0
	s_mov_b32 m0, s42
	s_nop 0
	global_load_lds_dwordx4 v[116:117], off
	s_mov_b32 m0, s99
	s_add_i32 s37, s37, 1
.Lmb3_skVBn:
	s_waitcnt lgkmcnt(8)
	v_mfma_f32_32x32x16_bf16 v[16:31], v[108:111], v[186:189], v[16:31]
	v_mfma_f32_32x32x16_bf16 v[16:31], v[104:107], v[190:193], v[16:31]
	v_mfma_f32_32x32x16_bf16 v[16:31], v[100:103], v[194:197], v[16:31]
	v_mfma_f32_32x32x16_bf16 v[16:31], v[96:99], v[198:201], v[16:31]
	v_mfma_f32_32x32x16_bf16 v[32:47], v[108:111], v[202:205], v[32:47]
	v_mfma_f32_32x32x16_bf16 v[32:47], v[104:107], v[206:209], v[32:47]
	v_mfma_f32_32x32x16_bf16 v[32:47], v[100:103], v[210:213], v[32:47]
	v_mfma_f32_32x32x16_bf16 v[32:47], v[96:99], v[214:217], v[32:47]
	s_lshr_b32 s42, s30, 2
	s_cmp_eq_u32 s42, s93
	s_cselect_b64 s[10:11], -1, 0
	s_lshl_b32 s42, 1, s42
	v_and_b32_e32 v96, s42, v129
	v_cmp_ne_u32_e32 vcc, 0, v96
	s_or_b64 vcc, s[10:11], vcc
	s_nop 0
	v_cndmask_b32_e32 v96, v127, v112, vcc
	v_lshl_add_u32 v96, v96, 2, 0
	v_add_u32_e32 v104, 0x1d000, v96
	ds_read2_b32 v[96:97], v104 offset0:58 offset1:59
	ds_read2_b32 v[98:99], v104 offset0:26 offset1:27
	ds_read2_b32 v[100:101], v104 offset0:56 offset1:57
	s_waitcnt lgkmcnt(2)
	v_pk_add_f32 v[236:237], v[236:237], v[96:97] op_sel:[0,1] op_sel_hi:[1,0]
	ds_read2_b32 v[96:97], v104 offset0:24 offset1:25
	s_waitcnt lgkmcnt(2)
	v_pk_add_f32 v[134:135], v[134:135], v[98:99] op_sel:[0,1] op_sel_hi:[1,0]
	ds_read2_b32 v[98:99], v104 offset0:50 offset1:51
	s_waitcnt lgkmcnt(2)
	v_pk_add_f32 v[238:239], v[238:239], v[100:101] op_sel:[0,1] op_sel_hi:[1,0]
	ds_read2_b32 v[100:101], v104 offset0:18 offset1:19
	s_waitcnt lgkmcnt(1)
	v_pk_add_f32 v[240:241], v[240:241], v[98:99] op_sel:[0,1] op_sel_hi:[1,0]
	ds_read2_b32 v[98:99], v104 offset0:16 offset1:17
	s_waitcnt lgkmcnt(1)
	v_pk_add_f32 v[138:139], v[138:139], v[100:101] op_sel:[0,1] op_sel_hi:[1,0]
	ds_read2_b32 v[100:101], v104 offset0:42 offset1:43
	v_pk_add_f32 v[136:137], v[136:137], v[96:97] op_sel:[0,1] op_sel_hi:[1,0]
	ds_read2_b32 v[96:97], v104 offset0:48 offset1:49
	s_waitcnt lgkmcnt(1)
	v_pk_add_f32 v[244:245], v[244:245], v[100:101] op_sel:[0,1] op_sel_hi:[1,0]
	ds_read2_b32 v[100:101], v104 offset0:8 offset1:9
	s_waitcnt lgkmcnt(1)
	v_pk_add_f32 v[242:243], v[242:243], v[96:97] op_sel:[0,1] op_sel_hi:[1,0]
	ds_read2_b32 v[96:97], v104 offset0:10 offset1:11
	v_pk_add_f32 v[140:141], v[140:141], v[98:99] op_sel:[0,1] op_sel_hi:[1,0]
	ds_read2_b32 v[98:99], v104 offset0:40 offset1:41
	s_waitcnt lgkmcnt(2)
	v_pk_add_f32 v[144:145], v[144:145], v[100:101] op_sel:[0,1] op_sel_hi:[1,0]
	s_waitcnt lgkmcnt(1)
	v_pk_add_f32 v[142:143], v[142:143], v[96:97] op_sel:[0,1] op_sel_hi:[1,0]
	ds_read2_b32 v[96:97], v104 offset0:34 offset1:35
	s_waitcnt lgkmcnt(1)
	v_pk_add_f32 v[246:247], v[246:247], v[98:99] op_sel:[0,1] op_sel_hi:[1,0]
	ds_read2_b32 v[98:99], v104 offset0:2 offset1:3
	ds_read2_b32 v[102:103], v104 offset0:32 offset1:33
	ds_read2_b32 v[104:105], v104 offset1:1
	s_waitcnt lgkmcnt(3)
	v_pk_add_f32 v[248:249], v[248:249], v[96:97] op_sel:[0,1] op_sel_hi:[1,0]
	s_waitcnt lgkmcnt(2)
	v_pk_add_f32 v[146:147], v[146:147], v[98:99] op_sel:[0,1] op_sel_hi:[1,0]
	s_waitcnt lgkmcnt(1)
	v_pk_add_f32 v[250:251], v[250:251], v[102:103] op_sel:[0,1] op_sel_hi:[1,0]
	s_waitcnt lgkmcnt(0)
	v_pk_add_f32 v[148:149], v[148:149], v[104:105] op_sel:[0,1] op_sel_hi:[1,0]
	s_waitcnt lgkmcnt(0)
	v_mfma_f32_32x32x16_bf16 v[64:79], v[154:157], v[92:95], v[220:235]
	ds_read_b64_tr_b16 v[186:187], v218
	ds_read_b64_tr_b16 v[188:189], v218 offset:512
	ds_read_b64_tr_b16 v[190:191], v218 offset:1024
	ds_read_b64_tr_b16 v[192:193], v218 offset:1536
	ds_read_b64_tr_b16 v[194:195], v218 offset:2048
	ds_read_b64_tr_b16 v[196:197], v218 offset:2560
	ds_read_b64_tr_b16 v[198:199], v218 offset:3072
	ds_read_b64_tr_b16 v[200:201], v218 offset:3584
	ds_read_b64_tr_b16 v[202:203], v218 offset:4096
	ds_read_b64_tr_b16 v[204:205], v218 offset:4608
	ds_read_b64_tr_b16 v[206:207], v218 offset:5120
	v_mfma_f32_32x32x16_bf16 v[48:63], v[158:161], v[92:95], v[220:235]
	ds_read_b64_tr_b16 v[208:209], v218 offset:5632
	ds_read_b64_tr_b16 v[210:211], v218 offset:6144
	ds_read_b64_tr_b16 v[212:213], v218 offset:6656
	ds_read_b64_tr_b16 v[214:215], v218 offset:7168
	ds_read_b64_tr_b16 v[216:217], v218 offset:7680
	v_exp_f32_e32 v236, v236
	v_exp_f32_e32 v134, v134
	v_exp_f32_e32 v237, v237
	v_exp_f32_e32 v135, v135
	v_exp_f32_e32 v238, v238
	v_exp_f32_e32 v136, v136
	v_mfma_f32_32x32x16_bf16 v[64:79], v[162:165], v[88:91], v[64:79]
	v_exp_f32_e32 v239, v239
	v_exp_f32_e32 v137, v137
	v_add_f32_e32 v252, v134, v236
	v_exp_f32_e32 v240, v240
	v_exp_f32_e32 v138, v138
	v_add_f32_e32 v252, 0, v252
	v_add_f32_e32 v253, v135, v237
	v_exp_f32_e32 v241, v241
	v_exp_f32_e32 v139, v139
	v_add_f32_e32 v252, v253, v252
	v_add_f32_e32 v253, v136, v238
	v_mfma_f32_32x32x16_bf16 v[48:63], v[166:169], v[88:91], v[48:63]
	v_exp_f32_e32 v242, v242
	v_exp_f32_e32 v140, v140
	v_add_f32_e32 v252, v253, v252
	v_add_f32_e32 v253, v137, v239
	v_exp_f32_e32 v243, v243
	v_exp_f32_e32 v141, v141
	v_add_f32_e32 v252, v253, v252
	v_add_f32_e32 v253, v138, v240
	v_exp_f32_e32 v244, v244
	v_exp_f32_e32 v142, v142
	v_add_f32_e32 v252, v253, v252
	v_mfma_f32_32x32x16_bf16 v[64:79], v[170:173], v[84:87], v[64:79]
	v_add_f32_e32 v253, v139, v241
	v_exp_f32_e32 v245, v245
	v_exp_f32_e32 v143, v143
	v_add_f32_e32 v252, v253, v252
	v_add_f32_e32 v253, v140, v242
	v_exp_f32_e32 v246, v246
	v_exp_f32_e32 v144, v144
	v_add_f32_e32 v252, v253, v252
	v_add_f32_e32 v253, v141, v243
	v_exp_f32_e32 v247, v247
	v_exp_f32_e32 v145, v145
	v_mfma_f32_32x32x16_bf16 v[48:63], v[174:177], v[84:87], v[48:63]
	v_add_f32_e32 v252, v253, v252
	v_add_f32_e32 v253, v142, v244
	v_exp_f32_e32 v248, v248
	v_exp_f32_e32 v146, v146
	v_add_f32_e32 v252, v253, v252
	v_add_f32_e32 v253, v143, v245
	v_exp_f32_e32 v249, v249
	v_exp_f32_e32 v147, v147
	v_add_f32_e32 v252, v253, v252
	v_add_f32_e32 v253, v144, v246
	v_exp_f32_e32 v250, v250
	v_mfma_f32_32x32x16_bf16 v[64:79], v[178:181], v[80:83], v[64:79]
	v_exp_f32_e32 v148, v148
	v_add_f32_e32 v252, v253, v252
	v_add_f32_e32 v253, v145, v247
	v_exp_f32_e32 v251, v251
	v_exp_f32_e32 v149, v149
	v_add_f32_e32 v252, v253, v252
	v_add_f32_e32 v253, v146, v248
	v_add_f32_e32 v252, v253, v252
	v_add_f32_e32 v253, v147, v249
	v_add_f32_e32 v252, v253, v252
	v_add_f32_e32 v253, v148, v250
	v_mfma_f32_32x32x16_bf16 v[48:63], v[182:185], v[80:83], v[48:63]
	v_add_f32_e32 v252, v253, v252
	v_add_f32_e32 v253, v149, v251
	v_add_f32_e32 v252, v253, v252
	v_add_f32_e32 v131, v131, v252
	v_cvt_pk_bf16_f32 v108, v236, v237
	v_cvt_pk_bf16_f32 v109, v238, v239
	v_cvt_pk_bf16_f32 v110, v240, v241
	v_cvt_pk_bf16_f32 v111, v242, v243
	v_cvt_pk_bf16_f32 v104, v244, v245
	v_cvt_pk_bf16_f32 v105, v246, v247
	v_cvt_pk_bf16_f32 v106, v248, v249
	v_cvt_pk_bf16_f32 v107, v250, v251
	v_cvt_pk_bf16_f32 v100, v134, v135
	v_cvt_pk_bf16_f32 v101, v136, v137
	v_cvt_pk_bf16_f32 v102, v138, v139
	v_cvt_pk_bf16_f32 v103, v140, v141
	v_cvt_pk_bf16_f32 v96, v142, v143
	v_cvt_pk_bf16_f32 v97, v144, v145
	v_cvt_pk_bf16_f32 v98, v146, v147
	v_cvt_pk_bf16_f32 v99, v148, v149
	s_branch .Lmb3_B_tail
